# ssm_fixup rewritten by hand: all 46 loads per thread in flight before the first wait
# baseline (speedup 1.0000x reference)
.LBB0_322:
	s_ashr_i32 s37, s31, 5
	s_and_b32 s36, s31, 31
	v_cmp_gt_u32_e32 vcc, 0x1e0, v197
	s_and_saveexec_b64 s[40:41], vcc
	s_cbranch_execz .LBB0_341
	v_readlane_b32 s16, v254, 50
	v_readlane_b32 s17, v254, 51
	v_readlane_b32 s18, v254, 52
	v_readlane_b32 s19, v254, 53
	s_add_u32 s20, s92, 0x1e380000
	s_addc_u32 s21, s93, 0
	s_lshl_b32 s22, s37, 6
	s_mov_b32 s23, 0xd0000
	s_mov_b32 s42, 0xbfb8aa3b
	s_mov_b32 s43, 0xbfb8aa3b
	s_mov_b32 s44, 0x9000
	s_lshl_b32 s0, s36, 6
	s_lshr_b32 s1, s36, 3
	s_lshl_b32 s1, s1, 7
	s_add_i32 s2, s1, 0x7c0
	s_add_i32 s3, s1, 0x940
	v_mul_u32_u24_e32 v238, 0xcccd, v197
	v_lshrrev_b32_e32 v238, 21, v238
	v_mul_u32_u24_e32 v0, 40, v238
	v_sub_u32_e32 v239, v197, v0
	v_mov_b32_e32 v0, s3
	v_mov_b32_e32 v1, s2
	v_cmp_gt_u32_e32 vcc, 24, v239
	v_mov_b32_e32 v2, s0
	s_nop 1
	v_cndmask_b32_e32 v0, v0, v1, vcc
	v_cmp_gt_u32_e32 vcc, 8, v239
	s_nop 1
	v_cndmask_b32_e32 v0, v0, v2, vcc
	v_lshl_add_u32 v0, v239, 3, v0
	v_lshlrev_b32_e32 v240, 1, v0
	v_lshlrev_b32_e32 v241, 2, v0
	v_add_u32_e32 v242, 0x3000, v241
	v_add_u32_e32 v243, 0x6000, v241
	v_add_u32_e32 v244, 0x9000, v241
	global_load_dwordx4 v[4:7], v241, s[18:19]
	global_load_dwordx4 v[8:11], v241, s[18:19] offset:16
	global_load_dwordx4 v[12:15], v241, s[16:17]
	global_load_dwordx4 v[16:19], v241, s[16:17] offset:16
	global_load_dwordx4 v[20:23], v242, s[16:17]
	global_load_dwordx4 v[24:27], v242, s[16:17] offset:16
	global_load_dwordx4 v[28:31], v243, s[16:17]
	global_load_dwordx4 v[32:35], v243, s[16:17] offset:16
	global_load_dwordx4 v[36:39], v244, s[16:17]
	global_load_dwordx4 v[40:43], v244, s[16:17] offset:16
	v_add_u32_e32 v0, 0, v238
	v_add_u32_e32 v1, s22, v0
	v_add_u32_e32 v2, -1, v1
	v_mad_u32_u24 v1, v1, s44, v240
	v_add_u32_e32 v1, 0x4800, v1
	v_mad_u32_u24 v2, v2, s44, v240
	v_cmp_eq_u32_e32 vcc, 0, v0
	v_add_u32_e32 v0, 0x1580000, v240
	s_nop 0
	v_cndmask_b32_e32 v2, v2, v0, vcc
	global_load_dwordx4 v[44:47], v2, s[20:21]
	v_add_u32_e32 v2, 0x1800, v2
	global_load_dwordx4 v[48:51], v2, s[20:21]
	v_add_u32_e32 v2, 0x1800, v2
	global_load_dwordx4 v[52:55], v2, s[20:21]
	global_load_dwordx4 v[56:59], v1, s[20:21]
	v_add_u32_e32 v1, 0x1800, v1
	global_load_dwordx4 v[60:63], v1, s[20:21]
	v_add_u32_e32 v1, 0x1800, v1
	global_load_dwordx4 v[64:67], v1, s[20:21]
	v_add_u32_e32 v0, 12, v238
	v_add_u32_e32 v1, s22, v0
	v_add_u32_e32 v2, -1, v1
	v_mad_u32_u24 v1, v1, s44, v240
	v_add_u32_e32 v1, 0x4800, v1
	v_mad_u32_u24 v2, v2, s44, v240
	global_load_dwordx4 v[68:71], v2, s[20:21]
	v_add_u32_e32 v2, 0x1800, v2
	global_load_dwordx4 v[72:75], v2, s[20:21]
	v_add_u32_e32 v2, 0x1800, v2
	global_load_dwordx4 v[76:79], v2, s[20:21]
	global_load_dwordx4 v[80:83], v1, s[20:21]
	v_add_u32_e32 v1, 0x1800, v1
	global_load_dwordx4 v[84:87], v1, s[20:21]
	v_add_u32_e32 v1, 0x1800, v1
	global_load_dwordx4 v[88:91], v1, s[20:21]
	v_add_u32_e32 v0, 24, v238
	v_add_u32_e32 v1, s22, v0
	v_add_u32_e32 v2, -1, v1
	v_mad_u32_u24 v1, v1, s44, v240
	v_add_u32_e32 v1, 0x4800, v1
	v_mad_u32_u24 v2, v2, s44, v240
	global_load_dwordx4 v[92:95], v2, s[20:21]
	v_add_u32_e32 v2, 0x1800, v2
	global_load_dwordx4 v[96:99], v2, s[20:21]
	v_add_u32_e32 v2, 0x1800, v2
	global_load_dwordx4 v[100:103], v2, s[20:21]
	global_load_dwordx4 v[104:107], v1, s[20:21]
	v_add_u32_e32 v1, 0x1800, v1
	global_load_dwordx4 v[108:111], v1, s[20:21]
	v_add_u32_e32 v1, 0x1800, v1
	global_load_dwordx4 v[112:115], v1, s[20:21]
	v_add_u32_e32 v0, 36, v238
	v_add_u32_e32 v1, s22, v0
	v_add_u32_e32 v2, -1, v1
	v_mad_u32_u24 v1, v1, s44, v240
	v_add_u32_e32 v1, 0x4800, v1
	v_mad_u32_u24 v2, v2, s44, v240
	global_load_dwordx4 v[116:119], v2, s[20:21]
	v_add_u32_e32 v2, 0x1800, v2
	global_load_dwordx4 v[120:123], v2, s[20:21]
	v_add_u32_e32 v2, 0x1800, v2
	global_load_dwordx4 v[124:127], v2, s[20:21]
	global_load_dwordx4 v[128:131], v1, s[20:21]
	v_add_u32_e32 v1, 0x1800, v1
	global_load_dwordx4 v[132:135], v1, s[20:21]
	v_add_u32_e32 v1, 0x1800, v1
	global_load_dwordx4 v[136:139], v1, s[20:21]
	v_add_u32_e32 v0, 48, v238
	v_add_u32_e32 v1, s22, v0
	v_add_u32_e32 v2, -1, v1
	v_mad_u32_u24 v1, v1, s44, v240
	v_add_u32_e32 v1, 0x4800, v1
	v_mad_u32_u24 v2, v2, s44, v240
	global_load_dwordx4 v[140:143], v2, s[20:21]
	v_add_u32_e32 v2, 0x1800, v2
	global_load_dwordx4 v[144:147], v2, s[20:21]
	v_add_u32_e32 v2, 0x1800, v2
	global_load_dwordx4 v[148:151], v2, s[20:21]
	global_load_dwordx4 v[152:155], v1, s[20:21]
	v_add_u32_e32 v1, 0x1800, v1
	global_load_dwordx4 v[156:159], v1, s[20:21]
	v_add_u32_e32 v1, 0x1800, v1
	global_load_dwordx4 v[160:163], v1, s[20:21]
	v_add_u32_e32 v0, 60, v238
	v_min_u32_e32 v0, 64, v0
	v_cmp_eq_u32_e32 vcc, 64, v0
	v_add_u32_e32 v1, s22, v0
	v_mov_b32_e32 v2, 0x200
	v_cndmask_b32_e32 v1, v1, v2, vcc
	v_add_u32_e32 v2, -1, v1
	v_cndmask_b32_e32 v2, v2, v1, vcc
	v_mad_u32_u24 v1, v1, s44, v240
	v_add_u32_e32 v1, 0x4800, v1
	v_mad_u32_u24 v2, v2, s44, v240
	global_load_dwordx4 v[164:167], v2, s[20:21]
	v_add_u32_e32 v2, 0x1800, v2
	global_load_dwordx4 v[168:171], v2, s[20:21]
	v_add_u32_e32 v2, 0x1800, v2
	global_load_dwordx4 v[172:175], v2, s[20:21]
	global_load_dwordx4 v[176:179], v1, s[20:21]
	v_add_u32_e32 v1, 0x1800, v1
	global_load_dwordx4 v[180:183], v1, s[20:21]
	v_add_u32_e32 v1, 0x1800, v1
	global_load_dwordx4 v[184:187], v1, s[20:21]
	s_waitcnt vmcnt(30)
	v_lshlrev_b32_e32 v202, 16, v44
	v_and_b32_e32 v203, 0xffff0000, v44
	v_lshlrev_b32_e32 v204, 16, v48
	v_and_b32_e32 v205, 0xffff0000, v48
	v_lshlrev_b32_e32 v206, 16, v52
	v_and_b32_e32 v207, 0xffff0000, v52
	v_lshlrev_b32_e32 v208, 16, v56
	v_and_b32_e32 v209, 0xffff0000, v56
	v_lshlrev_b32_e32 v210, 16, v60
	v_and_b32_e32 v211, 0xffff0000, v60
	v_lshlrev_b32_e32 v212, 16, v64
	v_and_b32_e32 v213, 0xffff0000, v64
	v_pk_fma_f32 v[214:215], v[12:13], v[202:203], v[4:5]
	v_pk_fma_f32 v[216:217], v[12:13], v[204:205], v[4:5]
	v_pk_fma_f32 v[236:237], v[12:13], v[206:207], v[4:5]
	v_pk_fma_f32 v[214:215], v[20:21], v[204:205], v[214:215]
	v_pk_fma_f32 v[216:217], v[20:21], v[206:207], v[216:217]
	v_pk_fma_f32 v[236:237], v[20:21], v[208:209], v[236:237]
	v_pk_fma_f32 v[214:215], v[28:29], v[206:207], v[214:215]
	v_pk_fma_f32 v[216:217], v[28:29], v[208:209], v[216:217]
	v_pk_fma_f32 v[236:237], v[28:29], v[210:211], v[236:237]
	v_pk_fma_f32 v[214:215], v[36:37], v[208:209], v[214:215]
	v_pk_fma_f32 v[216:217], v[36:37], v[210:211], v[216:217]
	v_pk_fma_f32 v[236:237], v[36:37], v[212:213], v[236:237]
	v_pk_mul_f32 v[202:203], v[214:215], s[42:43]
	v_pk_mul_f32 v[204:205], v[216:217], s[42:43]
	v_pk_mul_f32 v[206:207], v[236:237], s[42:43]
	v_exp_f32_e32 v202, v202
	v_exp_f32_e32 v203, v203
	v_exp_f32_e32 v204, v204
	v_exp_f32_e32 v205, v205
	v_exp_f32_e32 v206, v206
	v_exp_f32_e32 v207, v207
	s_nop 0
	v_pk_add_f32 v[202:203], v[202:203], 1.0 op_sel_hi:[1,0]
	v_pk_add_f32 v[204:205], v[204:205], 1.0 op_sel_hi:[1,0]
	v_pk_add_f32 v[206:207], v[206:207], 1.0 op_sel_hi:[1,0]
	v_rcp_f32_e32 v202, v202
	v_rcp_f32_e32 v203, v203
	v_rcp_f32_e32 v204, v204
	v_rcp_f32_e32 v205, v205
	v_rcp_f32_e32 v206, v206
	v_rcp_f32_e32 v207, v207
	s_nop 0
	v_pk_mul_f32 v[214:215], v[214:215], v[202:203]
	v_pk_mul_f32 v[216:217], v[216:217], v[204:205]
	v_pk_mul_f32 v[236:237], v[236:237], v[206:207]
	v_cvt_pk_bf16_f32 v44, v214, v215
	v_cvt_pk_bf16_f32 v48, v216, v217
	v_cvt_pk_bf16_f32 v52, v236, v237
	v_lshlrev_b32_e32 v202, 16, v45
	v_and_b32_e32 v203, 0xffff0000, v45
	v_lshlrev_b32_e32 v204, 16, v49
	v_and_b32_e32 v205, 0xffff0000, v49
	v_lshlrev_b32_e32 v206, 16, v53
	v_and_b32_e32 v207, 0xffff0000, v53
	v_lshlrev_b32_e32 v208, 16, v57
	v_and_b32_e32 v209, 0xffff0000, v57
	v_lshlrev_b32_e32 v210, 16, v61
	v_and_b32_e32 v211, 0xffff0000, v61
	v_lshlrev_b32_e32 v212, 16, v65
	v_and_b32_e32 v213, 0xffff0000, v65
	v_pk_fma_f32 v[214:215], v[14:15], v[202:203], v[6:7]
	v_pk_fma_f32 v[216:217], v[14:15], v[204:205], v[6:7]
	v_pk_fma_f32 v[236:237], v[14:15], v[206:207], v[6:7]
	v_pk_fma_f32 v[214:215], v[22:23], v[204:205], v[214:215]
	v_pk_fma_f32 v[216:217], v[22:23], v[206:207], v[216:217]
	v_pk_fma_f32 v[236:237], v[22:23], v[208:209], v[236:237]
	v_pk_fma_f32 v[214:215], v[30:31], v[206:207], v[214:215]
	v_pk_fma_f32 v[216:217], v[30:31], v[208:209], v[216:217]
	v_pk_fma_f32 v[236:237], v[30:31], v[210:211], v[236:237]
	v_pk_fma_f32 v[214:215], v[38:39], v[208:209], v[214:215]
	v_pk_fma_f32 v[216:217], v[38:39], v[210:211], v[216:217]
	v_pk_fma_f32 v[236:237], v[38:39], v[212:213], v[236:237]
	v_pk_mul_f32 v[202:203], v[214:215], s[42:43]
	v_pk_mul_f32 v[204:205], v[216:217], s[42:43]
	v_pk_mul_f32 v[206:207], v[236:237], s[42:43]
	v_exp_f32_e32 v202, v202
	v_exp_f32_e32 v203, v203
	v_exp_f32_e32 v204, v204
	v_exp_f32_e32 v205, v205
	v_exp_f32_e32 v206, v206
	v_exp_f32_e32 v207, v207
	s_nop 0
	v_pk_add_f32 v[202:203], v[202:203], 1.0 op_sel_hi:[1,0]
	v_pk_add_f32 v[204:205], v[204:205], 1.0 op_sel_hi:[1,0]
	v_pk_add_f32 v[206:207], v[206:207], 1.0 op_sel_hi:[1,0]
	v_rcp_f32_e32 v202, v202
	v_rcp_f32_e32 v203, v203
	v_rcp_f32_e32 v204, v204
	v_rcp_f32_e32 v205, v205
	v_rcp_f32_e32 v206, v206
	v_rcp_f32_e32 v207, v207
	s_nop 0
	v_pk_mul_f32 v[214:215], v[214:215], v[202:203]
	v_pk_mul_f32 v[216:217], v[216:217], v[204:205]
	v_pk_mul_f32 v[236:237], v[236:237], v[206:207]
	v_cvt_pk_bf16_f32 v45, v214, v215
	v_cvt_pk_bf16_f32 v49, v216, v217
	v_cvt_pk_bf16_f32 v53, v236, v237
	v_lshlrev_b32_e32 v202, 16, v46
	v_and_b32_e32 v203, 0xffff0000, v46
	v_lshlrev_b32_e32 v204, 16, v50
	v_and_b32_e32 v205, 0xffff0000, v50
	v_lshlrev_b32_e32 v206, 16, v54
	v_and_b32_e32 v207, 0xffff0000, v54
	v_lshlrev_b32_e32 v208, 16, v58
	v_and_b32_e32 v209, 0xffff0000, v58
	v_lshlrev_b32_e32 v210, 16, v62
	v_and_b32_e32 v211, 0xffff0000, v62
	v_lshlrev_b32_e32 v212, 16, v66
	v_and_b32_e32 v213, 0xffff0000, v66
	v_pk_fma_f32 v[214:215], v[16:17], v[202:203], v[8:9]
	v_pk_fma_f32 v[216:217], v[16:17], v[204:205], v[8:9]
	v_pk_fma_f32 v[236:237], v[16:17], v[206:207], v[8:9]
	v_pk_fma_f32 v[214:215], v[24:25], v[204:205], v[214:215]
	v_pk_fma_f32 v[216:217], v[24:25], v[206:207], v[216:217]
	v_pk_fma_f32 v[236:237], v[24:25], v[208:209], v[236:237]
	v_pk_fma_f32 v[214:215], v[32:33], v[206:207], v[214:215]
	v_pk_fma_f32 v[216:217], v[32:33], v[208:209], v[216:217]
	v_pk_fma_f32 v[236:237], v[32:33], v[210:211], v[236:237]
	v_pk_fma_f32 v[214:215], v[40:41], v[208:209], v[214:215]
	v_pk_fma_f32 v[216:217], v[40:41], v[210:211], v[216:217]
	v_pk_fma_f32 v[236:237], v[40:41], v[212:213], v[236:237]
	v_pk_mul_f32 v[202:203], v[214:215], s[42:43]
	v_pk_mul_f32 v[204:205], v[216:217], s[42:43]
	v_pk_mul_f32 v[206:207], v[236:237], s[42:43]
	v_exp_f32_e32 v202, v202
	v_exp_f32_e32 v203, v203
	v_exp_f32_e32 v204, v204
	v_exp_f32_e32 v205, v205
	v_exp_f32_e32 v206, v206
	v_exp_f32_e32 v207, v207
	s_nop 0
	v_pk_add_f32 v[202:203], v[202:203], 1.0 op_sel_hi:[1,0]
	v_pk_add_f32 v[204:205], v[204:205], 1.0 op_sel_hi:[1,0]
	v_pk_add_f32 v[206:207], v[206:207], 1.0 op_sel_hi:[1,0]
	v_rcp_f32_e32 v202, v202
	v_rcp_f32_e32 v203, v203
	v_rcp_f32_e32 v204, v204
	v_rcp_f32_e32 v205, v205
	v_rcp_f32_e32 v206, v206
	v_rcp_f32_e32 v207, v207
	s_nop 0
	v_pk_mul_f32 v[214:215], v[214:215], v[202:203]
	v_pk_mul_f32 v[216:217], v[216:217], v[204:205]
	v_pk_mul_f32 v[236:237], v[236:237], v[206:207]
	v_cvt_pk_bf16_f32 v46, v214, v215
	v_cvt_pk_bf16_f32 v50, v216, v217
	v_cvt_pk_bf16_f32 v54, v236, v237
	v_lshlrev_b32_e32 v202, 16, v47
	v_and_b32_e32 v203, 0xffff0000, v47
	v_lshlrev_b32_e32 v204, 16, v51
	v_and_b32_e32 v205, 0xffff0000, v51
	v_lshlrev_b32_e32 v206, 16, v55
	v_and_b32_e32 v207, 0xffff0000, v55
	v_lshlrev_b32_e32 v208, 16, v59
	v_and_b32_e32 v209, 0xffff0000, v59
	v_lshlrev_b32_e32 v210, 16, v63
	v_and_b32_e32 v211, 0xffff0000, v63
	v_lshlrev_b32_e32 v212, 16, v67
	v_and_b32_e32 v213, 0xffff0000, v67
	v_pk_fma_f32 v[214:215], v[18:19], v[202:203], v[10:11]
	v_pk_fma_f32 v[216:217], v[18:19], v[204:205], v[10:11]
	v_pk_fma_f32 v[236:237], v[18:19], v[206:207], v[10:11]
	v_pk_fma_f32 v[214:215], v[26:27], v[204:205], v[214:215]
	v_pk_fma_f32 v[216:217], v[26:27], v[206:207], v[216:217]
	v_pk_fma_f32 v[236:237], v[26:27], v[208:209], v[236:237]
	v_pk_fma_f32 v[214:215], v[34:35], v[206:207], v[214:215]
	v_pk_fma_f32 v[216:217], v[34:35], v[208:209], v[216:217]
	v_pk_fma_f32 v[236:237], v[34:35], v[210:211], v[236:237]
	v_pk_fma_f32 v[214:215], v[42:43], v[208:209], v[214:215]
	v_pk_fma_f32 v[216:217], v[42:43], v[210:211], v[216:217]
	v_pk_fma_f32 v[236:237], v[42:43], v[212:213], v[236:237]
	v_pk_mul_f32 v[202:203], v[214:215], s[42:43]
	v_pk_mul_f32 v[204:205], v[216:217], s[42:43]
	v_pk_mul_f32 v[206:207], v[236:237], s[42:43]
	v_exp_f32_e32 v202, v202
	v_exp_f32_e32 v203, v203
	v_exp_f32_e32 v204, v204
	v_exp_f32_e32 v205, v205
	v_exp_f32_e32 v206, v206
	v_exp_f32_e32 v207, v207
	s_nop 0
	v_pk_add_f32 v[202:203], v[202:203], 1.0 op_sel_hi:[1,0]
	v_pk_add_f32 v[204:205], v[204:205], 1.0 op_sel_hi:[1,0]
	v_pk_add_f32 v[206:207], v[206:207], 1.0 op_sel_hi:[1,0]
	v_rcp_f32_e32 v202, v202
	v_rcp_f32_e32 v203, v203
	v_rcp_f32_e32 v204, v204
	v_rcp_f32_e32 v205, v205
	v_rcp_f32_e32 v206, v206
	v_rcp_f32_e32 v207, v207
	s_nop 0
	v_pk_mul_f32 v[214:215], v[214:215], v[202:203]
	v_pk_mul_f32 v[216:217], v[216:217], v[204:205]
	v_pk_mul_f32 v[236:237], v[236:237], v[206:207]
	v_cvt_pk_bf16_f32 v47, v214, v215
	v_cvt_pk_bf16_f32 v51, v216, v217
	v_cvt_pk_bf16_f32 v55, v236, v237
	v_add_u32_e32 v0, 0, v238
	v_add_u32_e32 v1, s22, v0
	v_add_u32_e32 v2, 0x1000, v240
	v_mad_u32_u24 v1, v1, s23, v2
	global_store_dwordx4 v1, v[44:47], s[96:97]
	v_add_u32_e32 v1, 0x3400, v1
	global_store_dwordx4 v1, v[48:51], s[96:97]
	v_add_u32_e32 v1, 0x3400, v1
	global_store_dwordx4 v1, v[52:55], s[96:97]
	s_waitcnt vmcnt(27)
	v_lshlrev_b32_e32 v202, 16, v68
	v_and_b32_e32 v203, 0xffff0000, v68
	v_lshlrev_b32_e32 v204, 16, v72
	v_and_b32_e32 v205, 0xffff0000, v72
	v_lshlrev_b32_e32 v206, 16, v76
	v_and_b32_e32 v207, 0xffff0000, v76
	v_lshlrev_b32_e32 v208, 16, v80
	v_and_b32_e32 v209, 0xffff0000, v80
	v_lshlrev_b32_e32 v210, 16, v84
	v_and_b32_e32 v211, 0xffff0000, v84
	v_lshlrev_b32_e32 v212, 16, v88
	v_and_b32_e32 v213, 0xffff0000, v88
	v_pk_fma_f32 v[214:215], v[12:13], v[202:203], v[4:5]
	v_pk_fma_f32 v[216:217], v[12:13], v[204:205], v[4:5]
	v_pk_fma_f32 v[236:237], v[12:13], v[206:207], v[4:5]
	v_pk_fma_f32 v[214:215], v[20:21], v[204:205], v[214:215]
	v_pk_fma_f32 v[216:217], v[20:21], v[206:207], v[216:217]
	v_pk_fma_f32 v[236:237], v[20:21], v[208:209], v[236:237]
	v_pk_fma_f32 v[214:215], v[28:29], v[206:207], v[214:215]
	v_pk_fma_f32 v[216:217], v[28:29], v[208:209], v[216:217]
	v_pk_fma_f32 v[236:237], v[28:29], v[210:211], v[236:237]
	v_pk_fma_f32 v[214:215], v[36:37], v[208:209], v[214:215]
	v_pk_fma_f32 v[216:217], v[36:37], v[210:211], v[216:217]
	v_pk_fma_f32 v[236:237], v[36:37], v[212:213], v[236:237]
	v_pk_mul_f32 v[202:203], v[214:215], s[42:43]
	v_pk_mul_f32 v[204:205], v[216:217], s[42:43]
	v_pk_mul_f32 v[206:207], v[236:237], s[42:43]
	v_exp_f32_e32 v202, v202
	v_exp_f32_e32 v203, v203
	v_exp_f32_e32 v204, v204
	v_exp_f32_e32 v205, v205
	v_exp_f32_e32 v206, v206
	v_exp_f32_e32 v207, v207
	s_nop 0
	v_pk_add_f32 v[202:203], v[202:203], 1.0 op_sel_hi:[1,0]
	v_pk_add_f32 v[204:205], v[204:205], 1.0 op_sel_hi:[1,0]
	v_pk_add_f32 v[206:207], v[206:207], 1.0 op_sel_hi:[1,0]
	v_rcp_f32_e32 v202, v202
	v_rcp_f32_e32 v203, v203
	v_rcp_f32_e32 v204, v204
	v_rcp_f32_e32 v205, v205
	v_rcp_f32_e32 v206, v206
	v_rcp_f32_e32 v207, v207
	s_nop 0
	v_pk_mul_f32 v[214:215], v[214:215], v[202:203]
	v_pk_mul_f32 v[216:217], v[216:217], v[204:205]
	v_pk_mul_f32 v[236:237], v[236:237], v[206:207]
	v_cvt_pk_bf16_f32 v68, v214, v215
	v_cvt_pk_bf16_f32 v72, v216, v217
	v_cvt_pk_bf16_f32 v76, v236, v237
	v_lshlrev_b32_e32 v202, 16, v69
	v_and_b32_e32 v203, 0xffff0000, v69
	v_lshlrev_b32_e32 v204, 16, v73
	v_and_b32_e32 v205, 0xffff0000, v73
	v_lshlrev_b32_e32 v206, 16, v77
	v_and_b32_e32 v207, 0xffff0000, v77
	v_lshlrev_b32_e32 v208, 16, v81
	v_and_b32_e32 v209, 0xffff0000, v81
	v_lshlrev_b32_e32 v210, 16, v85
	v_and_b32_e32 v211, 0xffff0000, v85
	v_lshlrev_b32_e32 v212, 16, v89
	v_and_b32_e32 v213, 0xffff0000, v89
	v_pk_fma_f32 v[214:215], v[14:15], v[202:203], v[6:7]
	v_pk_fma_f32 v[216:217], v[14:15], v[204:205], v[6:7]
	v_pk_fma_f32 v[236:237], v[14:15], v[206:207], v[6:7]
	v_pk_fma_f32 v[214:215], v[22:23], v[204:205], v[214:215]
	v_pk_fma_f32 v[216:217], v[22:23], v[206:207], v[216:217]
	v_pk_fma_f32 v[236:237], v[22:23], v[208:209], v[236:237]
	v_pk_fma_f32 v[214:215], v[30:31], v[206:207], v[214:215]
	v_pk_fma_f32 v[216:217], v[30:31], v[208:209], v[216:217]
	v_pk_fma_f32 v[236:237], v[30:31], v[210:211], v[236:237]
	v_pk_fma_f32 v[214:215], v[38:39], v[208:209], v[214:215]
	v_pk_fma_f32 v[216:217], v[38:39], v[210:211], v[216:217]
	v_pk_fma_f32 v[236:237], v[38:39], v[212:213], v[236:237]
	v_pk_mul_f32 v[202:203], v[214:215], s[42:43]
	v_pk_mul_f32 v[204:205], v[216:217], s[42:43]
	v_pk_mul_f32 v[206:207], v[236:237], s[42:43]
	v_exp_f32_e32 v202, v202
	v_exp_f32_e32 v203, v203
	v_exp_f32_e32 v204, v204
	v_exp_f32_e32 v205, v205
	v_exp_f32_e32 v206, v206
	v_exp_f32_e32 v207, v207
	s_nop 0
	v_pk_add_f32 v[202:203], v[202:203], 1.0 op_sel_hi:[1,0]
	v_pk_add_f32 v[204:205], v[204:205], 1.0 op_sel_hi:[1,0]
	v_pk_add_f32 v[206:207], v[206:207], 1.0 op_sel_hi:[1,0]
	v_rcp_f32_e32 v202, v202
	v_rcp_f32_e32 v203, v203
	v_rcp_f32_e32 v204, v204
	v_rcp_f32_e32 v205, v205
	v_rcp_f32_e32 v206, v206
	v_rcp_f32_e32 v207, v207
	s_nop 0
	v_pk_mul_f32 v[214:215], v[214:215], v[202:203]
	v_pk_mul_f32 v[216:217], v[216:217], v[204:205]
	v_pk_mul_f32 v[236:237], v[236:237], v[206:207]
	v_cvt_pk_bf16_f32 v69, v214, v215
	v_cvt_pk_bf16_f32 v73, v216, v217
	v_cvt_pk_bf16_f32 v77, v236, v237
	v_lshlrev_b32_e32 v202, 16, v70
	v_and_b32_e32 v203, 0xffff0000, v70
	v_lshlrev_b32_e32 v204, 16, v74
	v_and_b32_e32 v205, 0xffff0000, v74
	v_lshlrev_b32_e32 v206, 16, v78
	v_and_b32_e32 v207, 0xffff0000, v78
	v_lshlrev_b32_e32 v208, 16, v82
	v_and_b32_e32 v209, 0xffff0000, v82
	v_lshlrev_b32_e32 v210, 16, v86
	v_and_b32_e32 v211, 0xffff0000, v86
	v_lshlrev_b32_e32 v212, 16, v90
	v_and_b32_e32 v213, 0xffff0000, v90
	v_pk_fma_f32 v[214:215], v[16:17], v[202:203], v[8:9]
	v_pk_fma_f32 v[216:217], v[16:17], v[204:205], v[8:9]
	v_pk_fma_f32 v[236:237], v[16:17], v[206:207], v[8:9]
	v_pk_fma_f32 v[214:215], v[24:25], v[204:205], v[214:215]
	v_pk_fma_f32 v[216:217], v[24:25], v[206:207], v[216:217]
	v_pk_fma_f32 v[236:237], v[24:25], v[208:209], v[236:237]
	v_pk_fma_f32 v[214:215], v[32:33], v[206:207], v[214:215]
	v_pk_fma_f32 v[216:217], v[32:33], v[208:209], v[216:217]
	v_pk_fma_f32 v[236:237], v[32:33], v[210:211], v[236:237]
	v_pk_fma_f32 v[214:215], v[40:41], v[208:209], v[214:215]
	v_pk_fma_f32 v[216:217], v[40:41], v[210:211], v[216:217]
	v_pk_fma_f32 v[236:237], v[40:41], v[212:213], v[236:237]
	v_pk_mul_f32 v[202:203], v[214:215], s[42:43]
	v_pk_mul_f32 v[204:205], v[216:217], s[42:43]
	v_pk_mul_f32 v[206:207], v[236:237], s[42:43]
	v_exp_f32_e32 v202, v202
	v_exp_f32_e32 v203, v203
	v_exp_f32_e32 v204, v204
	v_exp_f32_e32 v205, v205
	v_exp_f32_e32 v206, v206
	v_exp_f32_e32 v207, v207
	s_nop 0
	v_pk_add_f32 v[202:203], v[202:203], 1.0 op_sel_hi:[1,0]
	v_pk_add_f32 v[204:205], v[204:205], 1.0 op_sel_hi:[1,0]
	v_pk_add_f32 v[206:207], v[206:207], 1.0 op_sel_hi:[1,0]
	v_rcp_f32_e32 v202, v202
	v_rcp_f32_e32 v203, v203
	v_rcp_f32_e32 v204, v204
	v_rcp_f32_e32 v205, v205
	v_rcp_f32_e32 v206, v206
	v_rcp_f32_e32 v207, v207
	s_nop 0
	v_pk_mul_f32 v[214:215], v[214:215], v[202:203]
	v_pk_mul_f32 v[216:217], v[216:217], v[204:205]
	v_pk_mul_f32 v[236:237], v[236:237], v[206:207]
	v_cvt_pk_bf16_f32 v70, v214, v215
	v_cvt_pk_bf16_f32 v74, v216, v217
	v_cvt_pk_bf16_f32 v78, v236, v237
	v_lshlrev_b32_e32 v202, 16, v71
	v_and_b32_e32 v203, 0xffff0000, v71
	v_lshlrev_b32_e32 v204, 16, v75
	v_and_b32_e32 v205, 0xffff0000, v75
	v_lshlrev_b32_e32 v206, 16, v79
	v_and_b32_e32 v207, 0xffff0000, v79
	v_lshlrev_b32_e32 v208, 16, v83
	v_and_b32_e32 v209, 0xffff0000, v83
	v_lshlrev_b32_e32 v210, 16, v87
	v_and_b32_e32 v211, 0xffff0000, v87
	v_lshlrev_b32_e32 v212, 16, v91
	v_and_b32_e32 v213, 0xffff0000, v91
	v_pk_fma_f32 v[214:215], v[18:19], v[202:203], v[10:11]
	v_pk_fma_f32 v[216:217], v[18:19], v[204:205], v[10:11]
	v_pk_fma_f32 v[236:237], v[18:19], v[206:207], v[10:11]
	v_pk_fma_f32 v[214:215], v[26:27], v[204:205], v[214:215]
	v_pk_fma_f32 v[216:217], v[26:27], v[206:207], v[216:217]
	v_pk_fma_f32 v[236:237], v[26:27], v[208:209], v[236:237]
	v_pk_fma_f32 v[214:215], v[34:35], v[206:207], v[214:215]
	v_pk_fma_f32 v[216:217], v[34:35], v[208:209], v[216:217]
	v_pk_fma_f32 v[236:237], v[34:35], v[210:211], v[236:237]
	v_pk_fma_f32 v[214:215], v[42:43], v[208:209], v[214:215]
	v_pk_fma_f32 v[216:217], v[42:43], v[210:211], v[216:217]
	v_pk_fma_f32 v[236:237], v[42:43], v[212:213], v[236:237]
	v_pk_mul_f32 v[202:203], v[214:215], s[42:43]
	v_pk_mul_f32 v[204:205], v[216:217], s[42:43]
	v_pk_mul_f32 v[206:207], v[236:237], s[42:43]
	v_exp_f32_e32 v202, v202
	v_exp_f32_e32 v203, v203
	v_exp_f32_e32 v204, v204
	v_exp_f32_e32 v205, v205
	v_exp_f32_e32 v206, v206
	v_exp_f32_e32 v207, v207
	s_nop 0
	v_pk_add_f32 v[202:203], v[202:203], 1.0 op_sel_hi:[1,0]
	v_pk_add_f32 v[204:205], v[204:205], 1.0 op_sel_hi:[1,0]
	v_pk_add_f32 v[206:207], v[206:207], 1.0 op_sel_hi:[1,0]
	v_rcp_f32_e32 v202, v202
	v_rcp_f32_e32 v203, v203
	v_rcp_f32_e32 v204, v204
	v_rcp_f32_e32 v205, v205
	v_rcp_f32_e32 v206, v206
	v_rcp_f32_e32 v207, v207
	s_nop 0
	v_pk_mul_f32 v[214:215], v[214:215], v[202:203]
	v_pk_mul_f32 v[216:217], v[216:217], v[204:205]
	v_pk_mul_f32 v[236:237], v[236:237], v[206:207]
	v_cvt_pk_bf16_f32 v71, v214, v215
	v_cvt_pk_bf16_f32 v75, v216, v217
	v_cvt_pk_bf16_f32 v79, v236, v237
	v_add_u32_e32 v0, 12, v238
	v_add_u32_e32 v1, s22, v0
	v_add_u32_e32 v2, 0x1000, v240
	v_mad_u32_u24 v1, v1, s23, v2
	global_store_dwordx4 v1, v[68:71], s[96:97]
	v_add_u32_e32 v1, 0x3400, v1
	global_store_dwordx4 v1, v[72:75], s[96:97]
	v_add_u32_e32 v1, 0x3400, v1
	global_store_dwordx4 v1, v[76:79], s[96:97]
	s_waitcnt vmcnt(24)
	v_lshlrev_b32_e32 v202, 16, v92
	v_and_b32_e32 v203, 0xffff0000, v92
	v_lshlrev_b32_e32 v204, 16, v96
	v_and_b32_e32 v205, 0xffff0000, v96
	v_lshlrev_b32_e32 v206, 16, v100
	v_and_b32_e32 v207, 0xffff0000, v100
	v_lshlrev_b32_e32 v208, 16, v104
	v_and_b32_e32 v209, 0xffff0000, v104
	v_lshlrev_b32_e32 v210, 16, v108
	v_and_b32_e32 v211, 0xffff0000, v108
	v_lshlrev_b32_e32 v212, 16, v112
	v_and_b32_e32 v213, 0xffff0000, v112
	v_pk_fma_f32 v[214:215], v[12:13], v[202:203], v[4:5]
	v_pk_fma_f32 v[216:217], v[12:13], v[204:205], v[4:5]
	v_pk_fma_f32 v[236:237], v[12:13], v[206:207], v[4:5]
	v_pk_fma_f32 v[214:215], v[20:21], v[204:205], v[214:215]
	v_pk_fma_f32 v[216:217], v[20:21], v[206:207], v[216:217]
	v_pk_fma_f32 v[236:237], v[20:21], v[208:209], v[236:237]
	v_pk_fma_f32 v[214:215], v[28:29], v[206:207], v[214:215]
	v_pk_fma_f32 v[216:217], v[28:29], v[208:209], v[216:217]
	v_pk_fma_f32 v[236:237], v[28:29], v[210:211], v[236:237]
	v_pk_fma_f32 v[214:215], v[36:37], v[208:209], v[214:215]
	v_pk_fma_f32 v[216:217], v[36:37], v[210:211], v[216:217]
	v_pk_fma_f32 v[236:237], v[36:37], v[212:213], v[236:237]
	v_pk_mul_f32 v[202:203], v[214:215], s[42:43]
	v_pk_mul_f32 v[204:205], v[216:217], s[42:43]
	v_pk_mul_f32 v[206:207], v[236:237], s[42:43]
	v_exp_f32_e32 v202, v202
	v_exp_f32_e32 v203, v203
	v_exp_f32_e32 v204, v204
	v_exp_f32_e32 v205, v205
	v_exp_f32_e32 v206, v206
	v_exp_f32_e32 v207, v207
	s_nop 0
	v_pk_add_f32 v[202:203], v[202:203], 1.0 op_sel_hi:[1,0]
	v_pk_add_f32 v[204:205], v[204:205], 1.0 op_sel_hi:[1,0]
	v_pk_add_f32 v[206:207], v[206:207], 1.0 op_sel_hi:[1,0]
	v_rcp_f32_e32 v202, v202
	v_rcp_f32_e32 v203, v203
	v_rcp_f32_e32 v204, v204
	v_rcp_f32_e32 v205, v205
	v_rcp_f32_e32 v206, v206
	v_rcp_f32_e32 v207, v207
	s_nop 0
	v_pk_mul_f32 v[214:215], v[214:215], v[202:203]
	v_pk_mul_f32 v[216:217], v[216:217], v[204:205]
	v_pk_mul_f32 v[236:237], v[236:237], v[206:207]
	v_cvt_pk_bf16_f32 v92, v214, v215
	v_cvt_pk_bf16_f32 v96, v216, v217
	v_cvt_pk_bf16_f32 v100, v236, v237
	v_lshlrev_b32_e32 v202, 16, v93
	v_and_b32_e32 v203, 0xffff0000, v93
	v_lshlrev_b32_e32 v204, 16, v97
	v_and_b32_e32 v205, 0xffff0000, v97
	v_lshlrev_b32_e32 v206, 16, v101
	v_and_b32_e32 v207, 0xffff0000, v101
	v_lshlrev_b32_e32 v208, 16, v105
	v_and_b32_e32 v209, 0xffff0000, v105
	v_lshlrev_b32_e32 v210, 16, v109
	v_and_b32_e32 v211, 0xffff0000, v109
	v_lshlrev_b32_e32 v212, 16, v113
	v_and_b32_e32 v213, 0xffff0000, v113
	v_pk_fma_f32 v[214:215], v[14:15], v[202:203], v[6:7]
	v_pk_fma_f32 v[216:217], v[14:15], v[204:205], v[6:7]
	v_pk_fma_f32 v[236:237], v[14:15], v[206:207], v[6:7]
	v_pk_fma_f32 v[214:215], v[22:23], v[204:205], v[214:215]
	v_pk_fma_f32 v[216:217], v[22:23], v[206:207], v[216:217]
	v_pk_fma_f32 v[236:237], v[22:23], v[208:209], v[236:237]
	v_pk_fma_f32 v[214:215], v[30:31], v[206:207], v[214:215]
	v_pk_fma_f32 v[216:217], v[30:31], v[208:209], v[216:217]
	v_pk_fma_f32 v[236:237], v[30:31], v[210:211], v[236:237]
	v_pk_fma_f32 v[214:215], v[38:39], v[208:209], v[214:215]
	v_pk_fma_f32 v[216:217], v[38:39], v[210:211], v[216:217]
	v_pk_fma_f32 v[236:237], v[38:39], v[212:213], v[236:237]
	v_pk_mul_f32 v[202:203], v[214:215], s[42:43]
	v_pk_mul_f32 v[204:205], v[216:217], s[42:43]
	v_pk_mul_f32 v[206:207], v[236:237], s[42:43]
	v_exp_f32_e32 v202, v202
	v_exp_f32_e32 v203, v203
	v_exp_f32_e32 v204, v204
	v_exp_f32_e32 v205, v205
	v_exp_f32_e32 v206, v206
	v_exp_f32_e32 v207, v207
	s_nop 0
	v_pk_add_f32 v[202:203], v[202:203], 1.0 op_sel_hi:[1,0]
	v_pk_add_f32 v[204:205], v[204:205], 1.0 op_sel_hi:[1,0]
	v_pk_add_f32 v[206:207], v[206:207], 1.0 op_sel_hi:[1,0]
	v_rcp_f32_e32 v202, v202
	v_rcp_f32_e32 v203, v203
	v_rcp_f32_e32 v204, v204
	v_rcp_f32_e32 v205, v205
	v_rcp_f32_e32 v206, v206
	v_rcp_f32_e32 v207, v207
	s_nop 0
	v_pk_mul_f32 v[214:215], v[214:215], v[202:203]
	v_pk_mul_f32 v[216:217], v[216:217], v[204:205]
	v_pk_mul_f32 v[236:237], v[236:237], v[206:207]
	v_cvt_pk_bf16_f32 v93, v214, v215
	v_cvt_pk_bf16_f32 v97, v216, v217
	v_cvt_pk_bf16_f32 v101, v236, v237
	v_lshlrev_b32_e32 v202, 16, v94
	v_and_b32_e32 v203, 0xffff0000, v94
	v_lshlrev_b32_e32 v204, 16, v98
	v_and_b32_e32 v205, 0xffff0000, v98
	v_lshlrev_b32_e32 v206, 16, v102
	v_and_b32_e32 v207, 0xffff0000, v102
	v_lshlrev_b32_e32 v208, 16, v106
	v_and_b32_e32 v209, 0xffff0000, v106
	v_lshlrev_b32_e32 v210, 16, v110
	v_and_b32_e32 v211, 0xffff0000, v110
	v_lshlrev_b32_e32 v212, 16, v114
	v_and_b32_e32 v213, 0xffff0000, v114
	v_pk_fma_f32 v[214:215], v[16:17], v[202:203], v[8:9]
	v_pk_fma_f32 v[216:217], v[16:17], v[204:205], v[8:9]
	v_pk_fma_f32 v[236:237], v[16:17], v[206:207], v[8:9]
	v_pk_fma_f32 v[214:215], v[24:25], v[204:205], v[214:215]
	v_pk_fma_f32 v[216:217], v[24:25], v[206:207], v[216:217]
	v_pk_fma_f32 v[236:237], v[24:25], v[208:209], v[236:237]
	v_pk_fma_f32 v[214:215], v[32:33], v[206:207], v[214:215]
	v_pk_fma_f32 v[216:217], v[32:33], v[208:209], v[216:217]
	v_pk_fma_f32 v[236:237], v[32:33], v[210:211], v[236:237]
	v_pk_fma_f32 v[214:215], v[40:41], v[208:209], v[214:215]
	v_pk_fma_f32 v[216:217], v[40:41], v[210:211], v[216:217]
	v_pk_fma_f32 v[236:237], v[40:41], v[212:213], v[236:237]
	v_pk_mul_f32 v[202:203], v[214:215], s[42:43]
	v_pk_mul_f32 v[204:205], v[216:217], s[42:43]
	v_pk_mul_f32 v[206:207], v[236:237], s[42:43]
	v_exp_f32_e32 v202, v202
	v_exp_f32_e32 v203, v203
	v_exp_f32_e32 v204, v204
	v_exp_f32_e32 v205, v205
	v_exp_f32_e32 v206, v206
	v_exp_f32_e32 v207, v207
	s_nop 0
	v_pk_add_f32 v[202:203], v[202:203], 1.0 op_sel_hi:[1,0]
	v_pk_add_f32 v[204:205], v[204:205], 1.0 op_sel_hi:[1,0]
	v_pk_add_f32 v[206:207], v[206:207], 1.0 op_sel_hi:[1,0]
	v_rcp_f32_e32 v202, v202
	v_rcp_f32_e32 v203, v203
	v_rcp_f32_e32 v204, v204
	v_rcp_f32_e32 v205, v205
	v_rcp_f32_e32 v206, v206
	v_rcp_f32_e32 v207, v207
	s_nop 0
	v_pk_mul_f32 v[214:215], v[214:215], v[202:203]
	v_pk_mul_f32 v[216:217], v[216:217], v[204:205]
	v_pk_mul_f32 v[236:237], v[236:237], v[206:207]
	v_cvt_pk_bf16_f32 v94, v214, v215
	v_cvt_pk_bf16_f32 v98, v216, v217
	v_cvt_pk_bf16_f32 v102, v236, v237
	v_lshlrev_b32_e32 v202, 16, v95
	v_and_b32_e32 v203, 0xffff0000, v95
	v_lshlrev_b32_e32 v204, 16, v99
	v_and_b32_e32 v205, 0xffff0000, v99
	v_lshlrev_b32_e32 v206, 16, v103
	v_and_b32_e32 v207, 0xffff0000, v103
	v_lshlrev_b32_e32 v208, 16, v107
	v_and_b32_e32 v209, 0xffff0000, v107
	v_lshlrev_b32_e32 v210, 16, v111
	v_and_b32_e32 v211, 0xffff0000, v111
	v_lshlrev_b32_e32 v212, 16, v115
	v_and_b32_e32 v213, 0xffff0000, v115
	v_pk_fma_f32 v[214:215], v[18:19], v[202:203], v[10:11]
	v_pk_fma_f32 v[216:217], v[18:19], v[204:205], v[10:11]
	v_pk_fma_f32 v[236:237], v[18:19], v[206:207], v[10:11]
	v_pk_fma_f32 v[214:215], v[26:27], v[204:205], v[214:215]
	v_pk_fma_f32 v[216:217], v[26:27], v[206:207], v[216:217]
	v_pk_fma_f32 v[236:237], v[26:27], v[208:209], v[236:237]
	v_pk_fma_f32 v[214:215], v[34:35], v[206:207], v[214:215]
	v_pk_fma_f32 v[216:217], v[34:35], v[208:209], v[216:217]
	v_pk_fma_f32 v[236:237], v[34:35], v[210:211], v[236:237]
	v_pk_fma_f32 v[214:215], v[42:43], v[208:209], v[214:215]
	v_pk_fma_f32 v[216:217], v[42:43], v[210:211], v[216:217]
	v_pk_fma_f32 v[236:237], v[42:43], v[212:213], v[236:237]
	v_pk_mul_f32 v[202:203], v[214:215], s[42:43]
	v_pk_mul_f32 v[204:205], v[216:217], s[42:43]
	v_pk_mul_f32 v[206:207], v[236:237], s[42:43]
	v_exp_f32_e32 v202, v202
	v_exp_f32_e32 v203, v203
	v_exp_f32_e32 v204, v204
	v_exp_f32_e32 v205, v205
	v_exp_f32_e32 v206, v206
	v_exp_f32_e32 v207, v207
	s_nop 0
	v_pk_add_f32 v[202:203], v[202:203], 1.0 op_sel_hi:[1,0]
	v_pk_add_f32 v[204:205], v[204:205], 1.0 op_sel_hi:[1,0]
	v_pk_add_f32 v[206:207], v[206:207], 1.0 op_sel_hi:[1,0]
	v_rcp_f32_e32 v202, v202
	v_rcp_f32_e32 v203, v203
	v_rcp_f32_e32 v204, v204
	v_rcp_f32_e32 v205, v205
	v_rcp_f32_e32 v206, v206
	v_rcp_f32_e32 v207, v207
	s_nop 0
	v_pk_mul_f32 v[214:215], v[214:215], v[202:203]
	v_pk_mul_f32 v[216:217], v[216:217], v[204:205]
	v_pk_mul_f32 v[236:237], v[236:237], v[206:207]
	v_cvt_pk_bf16_f32 v95, v214, v215
	v_cvt_pk_bf16_f32 v99, v216, v217
	v_cvt_pk_bf16_f32 v103, v236, v237
	v_add_u32_e32 v0, 24, v238
	v_add_u32_e32 v1, s22, v0
	v_add_u32_e32 v2, 0x1000, v240
	v_mad_u32_u24 v1, v1, s23, v2
	global_store_dwordx4 v1, v[92:95], s[96:97]
	v_add_u32_e32 v1, 0x3400, v1
	global_store_dwordx4 v1, v[96:99], s[96:97]
	v_add_u32_e32 v1, 0x3400, v1
	global_store_dwordx4 v1, v[100:103], s[96:97]
	s_waitcnt vmcnt(21)
	v_lshlrev_b32_e32 v202, 16, v116
	v_and_b32_e32 v203, 0xffff0000, v116
	v_lshlrev_b32_e32 v204, 16, v120
	v_and_b32_e32 v205, 0xffff0000, v120
	v_lshlrev_b32_e32 v206, 16, v124
	v_and_b32_e32 v207, 0xffff0000, v124
	v_lshlrev_b32_e32 v208, 16, v128
	v_and_b32_e32 v209, 0xffff0000, v128
	v_lshlrev_b32_e32 v210, 16, v132
	v_and_b32_e32 v211, 0xffff0000, v132
	v_lshlrev_b32_e32 v212, 16, v136
	v_and_b32_e32 v213, 0xffff0000, v136
	v_pk_fma_f32 v[214:215], v[12:13], v[202:203], v[4:5]
	v_pk_fma_f32 v[216:217], v[12:13], v[204:205], v[4:5]
	v_pk_fma_f32 v[236:237], v[12:13], v[206:207], v[4:5]
	v_pk_fma_f32 v[214:215], v[20:21], v[204:205], v[214:215]
	v_pk_fma_f32 v[216:217], v[20:21], v[206:207], v[216:217]
	v_pk_fma_f32 v[236:237], v[20:21], v[208:209], v[236:237]
	v_pk_fma_f32 v[214:215], v[28:29], v[206:207], v[214:215]
	v_pk_fma_f32 v[216:217], v[28:29], v[208:209], v[216:217]
	v_pk_fma_f32 v[236:237], v[28:29], v[210:211], v[236:237]
	v_pk_fma_f32 v[214:215], v[36:37], v[208:209], v[214:215]
	v_pk_fma_f32 v[216:217], v[36:37], v[210:211], v[216:217]
	v_pk_fma_f32 v[236:237], v[36:37], v[212:213], v[236:237]
	v_pk_mul_f32 v[202:203], v[214:215], s[42:43]
	v_pk_mul_f32 v[204:205], v[216:217], s[42:43]
	v_pk_mul_f32 v[206:207], v[236:237], s[42:43]
	v_exp_f32_e32 v202, v202
	v_exp_f32_e32 v203, v203
	v_exp_f32_e32 v204, v204
	v_exp_f32_e32 v205, v205
	v_exp_f32_e32 v206, v206
	v_exp_f32_e32 v207, v207
	s_nop 0
	v_pk_add_f32 v[202:203], v[202:203], 1.0 op_sel_hi:[1,0]
	v_pk_add_f32 v[204:205], v[204:205], 1.0 op_sel_hi:[1,0]
	v_pk_add_f32 v[206:207], v[206:207], 1.0 op_sel_hi:[1,0]
	v_rcp_f32_e32 v202, v202
	v_rcp_f32_e32 v203, v203
	v_rcp_f32_e32 v204, v204
	v_rcp_f32_e32 v205, v205
	v_rcp_f32_e32 v206, v206
	v_rcp_f32_e32 v207, v207
	s_nop 0
	v_pk_mul_f32 v[214:215], v[214:215], v[202:203]
	v_pk_mul_f32 v[216:217], v[216:217], v[204:205]
	v_pk_mul_f32 v[236:237], v[236:237], v[206:207]
	v_cvt_pk_bf16_f32 v116, v214, v215
	v_cvt_pk_bf16_f32 v120, v216, v217
	v_cvt_pk_bf16_f32 v124, v236, v237
	v_lshlrev_b32_e32 v202, 16, v117
	v_and_b32_e32 v203, 0xffff0000, v117
	v_lshlrev_b32_e32 v204, 16, v121
	v_and_b32_e32 v205, 0xffff0000, v121
	v_lshlrev_b32_e32 v206, 16, v125
	v_and_b32_e32 v207, 0xffff0000, v125
	v_lshlrev_b32_e32 v208, 16, v129
	v_and_b32_e32 v209, 0xffff0000, v129
	v_lshlrev_b32_e32 v210, 16, v133
	v_and_b32_e32 v211, 0xffff0000, v133
	v_lshlrev_b32_e32 v212, 16, v137
	v_and_b32_e32 v213, 0xffff0000, v137
	v_pk_fma_f32 v[214:215], v[14:15], v[202:203], v[6:7]
	v_pk_fma_f32 v[216:217], v[14:15], v[204:205], v[6:7]
	v_pk_fma_f32 v[236:237], v[14:15], v[206:207], v[6:7]
	v_pk_fma_f32 v[214:215], v[22:23], v[204:205], v[214:215]
	v_pk_fma_f32 v[216:217], v[22:23], v[206:207], v[216:217]
	v_pk_fma_f32 v[236:237], v[22:23], v[208:209], v[236:237]
	v_pk_fma_f32 v[214:215], v[30:31], v[206:207], v[214:215]
	v_pk_fma_f32 v[216:217], v[30:31], v[208:209], v[216:217]
	v_pk_fma_f32 v[236:237], v[30:31], v[210:211], v[236:237]
	v_pk_fma_f32 v[214:215], v[38:39], v[208:209], v[214:215]
	v_pk_fma_f32 v[216:217], v[38:39], v[210:211], v[216:217]
	v_pk_fma_f32 v[236:237], v[38:39], v[212:213], v[236:237]
	v_pk_mul_f32 v[202:203], v[214:215], s[42:43]
	v_pk_mul_f32 v[204:205], v[216:217], s[42:43]
	v_pk_mul_f32 v[206:207], v[236:237], s[42:43]
	v_exp_f32_e32 v202, v202
	v_exp_f32_e32 v203, v203
	v_exp_f32_e32 v204, v204
	v_exp_f32_e32 v205, v205
	v_exp_f32_e32 v206, v206
	v_exp_f32_e32 v207, v207
	s_nop 0
	v_pk_add_f32 v[202:203], v[202:203], 1.0 op_sel_hi:[1,0]
	v_pk_add_f32 v[204:205], v[204:205], 1.0 op_sel_hi:[1,0]
	v_pk_add_f32 v[206:207], v[206:207], 1.0 op_sel_hi:[1,0]
	v_rcp_f32_e32 v202, v202
	v_rcp_f32_e32 v203, v203
	v_rcp_f32_e32 v204, v204
	v_rcp_f32_e32 v205, v205
	v_rcp_f32_e32 v206, v206
	v_rcp_f32_e32 v207, v207
	s_nop 0
	v_pk_mul_f32 v[214:215], v[214:215], v[202:203]
	v_pk_mul_f32 v[216:217], v[216:217], v[204:205]
	v_pk_mul_f32 v[236:237], v[236:237], v[206:207]
	v_cvt_pk_bf16_f32 v117, v214, v215
	v_cvt_pk_bf16_f32 v121, v216, v217
	v_cvt_pk_bf16_f32 v125, v236, v237
	v_lshlrev_b32_e32 v202, 16, v118
	v_and_b32_e32 v203, 0xffff0000, v118
	v_lshlrev_b32_e32 v204, 16, v122
	v_and_b32_e32 v205, 0xffff0000, v122
	v_lshlrev_b32_e32 v206, 16, v126
	v_and_b32_e32 v207, 0xffff0000, v126
	v_lshlrev_b32_e32 v208, 16, v130
	v_and_b32_e32 v209, 0xffff0000, v130
	v_lshlrev_b32_e32 v210, 16, v134
	v_and_b32_e32 v211, 0xffff0000, v134
	v_lshlrev_b32_e32 v212, 16, v138
	v_and_b32_e32 v213, 0xffff0000, v138
	v_pk_fma_f32 v[214:215], v[16:17], v[202:203], v[8:9]
	v_pk_fma_f32 v[216:217], v[16:17], v[204:205], v[8:9]
	v_pk_fma_f32 v[236:237], v[16:17], v[206:207], v[8:9]
	v_pk_fma_f32 v[214:215], v[24:25], v[204:205], v[214:215]
	v_pk_fma_f32 v[216:217], v[24:25], v[206:207], v[216:217]
	v_pk_fma_f32 v[236:237], v[24:25], v[208:209], v[236:237]
	v_pk_fma_f32 v[214:215], v[32:33], v[206:207], v[214:215]
	v_pk_fma_f32 v[216:217], v[32:33], v[208:209], v[216:217]
	v_pk_fma_f32 v[236:237], v[32:33], v[210:211], v[236:237]
	v_pk_fma_f32 v[214:215], v[40:41], v[208:209], v[214:215]
	v_pk_fma_f32 v[216:217], v[40:41], v[210:211], v[216:217]
	v_pk_fma_f32 v[236:237], v[40:41], v[212:213], v[236:237]
	v_pk_mul_f32 v[202:203], v[214:215], s[42:43]
	v_pk_mul_f32 v[204:205], v[216:217], s[42:43]
	v_pk_mul_f32 v[206:207], v[236:237], s[42:43]
	v_exp_f32_e32 v202, v202
	v_exp_f32_e32 v203, v203
	v_exp_f32_e32 v204, v204
	v_exp_f32_e32 v205, v205
	v_exp_f32_e32 v206, v206
	v_exp_f32_e32 v207, v207
	s_nop 0
	v_pk_add_f32 v[202:203], v[202:203], 1.0 op_sel_hi:[1,0]
	v_pk_add_f32 v[204:205], v[204:205], 1.0 op_sel_hi:[1,0]
	v_pk_add_f32 v[206:207], v[206:207], 1.0 op_sel_hi:[1,0]
	v_rcp_f32_e32 v202, v202
	v_rcp_f32_e32 v203, v203
	v_rcp_f32_e32 v204, v204
	v_rcp_f32_e32 v205, v205
	v_rcp_f32_e32 v206, v206
	v_rcp_f32_e32 v207, v207
	s_nop 0
	v_pk_mul_f32 v[214:215], v[214:215], v[202:203]
	v_pk_mul_f32 v[216:217], v[216:217], v[204:205]
	v_pk_mul_f32 v[236:237], v[236:237], v[206:207]
	v_cvt_pk_bf16_f32 v118, v214, v215
	v_cvt_pk_bf16_f32 v122, v216, v217
	v_cvt_pk_bf16_f32 v126, v236, v237
	v_lshlrev_b32_e32 v202, 16, v119
	v_and_b32_e32 v203, 0xffff0000, v119
	v_lshlrev_b32_e32 v204, 16, v123
	v_and_b32_e32 v205, 0xffff0000, v123
	v_lshlrev_b32_e32 v206, 16, v127
	v_and_b32_e32 v207, 0xffff0000, v127
	v_lshlrev_b32_e32 v208, 16, v131
	v_and_b32_e32 v209, 0xffff0000, v131
	v_lshlrev_b32_e32 v210, 16, v135
	v_and_b32_e32 v211, 0xffff0000, v135
	v_lshlrev_b32_e32 v212, 16, v139
	v_and_b32_e32 v213, 0xffff0000, v139
	v_pk_fma_f32 v[214:215], v[18:19], v[202:203], v[10:11]
	v_pk_fma_f32 v[216:217], v[18:19], v[204:205], v[10:11]
	v_pk_fma_f32 v[236:237], v[18:19], v[206:207], v[10:11]
	v_pk_fma_f32 v[214:215], v[26:27], v[204:205], v[214:215]
	v_pk_fma_f32 v[216:217], v[26:27], v[206:207], v[216:217]
	v_pk_fma_f32 v[236:237], v[26:27], v[208:209], v[236:237]
	v_pk_fma_f32 v[214:215], v[34:35], v[206:207], v[214:215]
	v_pk_fma_f32 v[216:217], v[34:35], v[208:209], v[216:217]
	v_pk_fma_f32 v[236:237], v[34:35], v[210:211], v[236:237]
	v_pk_fma_f32 v[214:215], v[42:43], v[208:209], v[214:215]
	v_pk_fma_f32 v[216:217], v[42:43], v[210:211], v[216:217]
	v_pk_fma_f32 v[236:237], v[42:43], v[212:213], v[236:237]
	v_pk_mul_f32 v[202:203], v[214:215], s[42:43]
	v_pk_mul_f32 v[204:205], v[216:217], s[42:43]
	v_pk_mul_f32 v[206:207], v[236:237], s[42:43]
	v_exp_f32_e32 v202, v202
	v_exp_f32_e32 v203, v203
	v_exp_f32_e32 v204, v204
	v_exp_f32_e32 v205, v205
	v_exp_f32_e32 v206, v206
	v_exp_f32_e32 v207, v207
	s_nop 0
	v_pk_add_f32 v[202:203], v[202:203], 1.0 op_sel_hi:[1,0]
	v_pk_add_f32 v[204:205], v[204:205], 1.0 op_sel_hi:[1,0]
	v_pk_add_f32 v[206:207], v[206:207], 1.0 op_sel_hi:[1,0]
	v_rcp_f32_e32 v202, v202
	v_rcp_f32_e32 v203, v203
	v_rcp_f32_e32 v204, v204
	v_rcp_f32_e32 v205, v205
	v_rcp_f32_e32 v206, v206
	v_rcp_f32_e32 v207, v207
	s_nop 0
	v_pk_mul_f32 v[214:215], v[214:215], v[202:203]
	v_pk_mul_f32 v[216:217], v[216:217], v[204:205]
	v_pk_mul_f32 v[236:237], v[236:237], v[206:207]
	v_cvt_pk_bf16_f32 v119, v214, v215
	v_cvt_pk_bf16_f32 v123, v216, v217
	v_cvt_pk_bf16_f32 v127, v236, v237
	v_add_u32_e32 v0, 36, v238
	v_add_u32_e32 v1, s22, v0
	v_add_u32_e32 v2, 0x1000, v240
	v_mad_u32_u24 v1, v1, s23, v2
	global_store_dwordx4 v1, v[116:119], s[96:97]
	v_add_u32_e32 v1, 0x3400, v1
	global_store_dwordx4 v1, v[120:123], s[96:97]
	v_add_u32_e32 v1, 0x3400, v1
	global_store_dwordx4 v1, v[124:127], s[96:97]
	s_waitcnt vmcnt(18)
	v_lshlrev_b32_e32 v202, 16, v140
	v_and_b32_e32 v203, 0xffff0000, v140
	v_lshlrev_b32_e32 v204, 16, v144
	v_and_b32_e32 v205, 0xffff0000, v144
	v_lshlrev_b32_e32 v206, 16, v148
	v_and_b32_e32 v207, 0xffff0000, v148
	v_lshlrev_b32_e32 v208, 16, v152
	v_and_b32_e32 v209, 0xffff0000, v152
	v_lshlrev_b32_e32 v210, 16, v156
	v_and_b32_e32 v211, 0xffff0000, v156
	v_lshlrev_b32_e32 v212, 16, v160
	v_and_b32_e32 v213, 0xffff0000, v160
	v_pk_fma_f32 v[214:215], v[12:13], v[202:203], v[4:5]
	v_pk_fma_f32 v[216:217], v[12:13], v[204:205], v[4:5]
	v_pk_fma_f32 v[236:237], v[12:13], v[206:207], v[4:5]
	v_pk_fma_f32 v[214:215], v[20:21], v[204:205], v[214:215]
	v_pk_fma_f32 v[216:217], v[20:21], v[206:207], v[216:217]
	v_pk_fma_f32 v[236:237], v[20:21], v[208:209], v[236:237]
	v_pk_fma_f32 v[214:215], v[28:29], v[206:207], v[214:215]
	v_pk_fma_f32 v[216:217], v[28:29], v[208:209], v[216:217]
	v_pk_fma_f32 v[236:237], v[28:29], v[210:211], v[236:237]
	v_pk_fma_f32 v[214:215], v[36:37], v[208:209], v[214:215]
	v_pk_fma_f32 v[216:217], v[36:37], v[210:211], v[216:217]
	v_pk_fma_f32 v[236:237], v[36:37], v[212:213], v[236:237]
	v_pk_mul_f32 v[202:203], v[214:215], s[42:43]
	v_pk_mul_f32 v[204:205], v[216:217], s[42:43]
	v_pk_mul_f32 v[206:207], v[236:237], s[42:43]
	v_exp_f32_e32 v202, v202
	v_exp_f32_e32 v203, v203
	v_exp_f32_e32 v204, v204
	v_exp_f32_e32 v205, v205
	v_exp_f32_e32 v206, v206
	v_exp_f32_e32 v207, v207
	s_nop 0
	v_pk_add_f32 v[202:203], v[202:203], 1.0 op_sel_hi:[1,0]
	v_pk_add_f32 v[204:205], v[204:205], 1.0 op_sel_hi:[1,0]
	v_pk_add_f32 v[206:207], v[206:207], 1.0 op_sel_hi:[1,0]
	v_rcp_f32_e32 v202, v202
	v_rcp_f32_e32 v203, v203
	v_rcp_f32_e32 v204, v204
	v_rcp_f32_e32 v205, v205
	v_rcp_f32_e32 v206, v206
	v_rcp_f32_e32 v207, v207
	s_nop 0
	v_pk_mul_f32 v[214:215], v[214:215], v[202:203]
	v_pk_mul_f32 v[216:217], v[216:217], v[204:205]
	v_pk_mul_f32 v[236:237], v[236:237], v[206:207]
	v_cvt_pk_bf16_f32 v140, v214, v215
	v_cvt_pk_bf16_f32 v144, v216, v217
	v_cvt_pk_bf16_f32 v148, v236, v237
	v_lshlrev_b32_e32 v202, 16, v141
	v_and_b32_e32 v203, 0xffff0000, v141
	v_lshlrev_b32_e32 v204, 16, v145
	v_and_b32_e32 v205, 0xffff0000, v145
	v_lshlrev_b32_e32 v206, 16, v149
	v_and_b32_e32 v207, 0xffff0000, v149
	v_lshlrev_b32_e32 v208, 16, v153
	v_and_b32_e32 v209, 0xffff0000, v153
	v_lshlrev_b32_e32 v210, 16, v157
	v_and_b32_e32 v211, 0xffff0000, v157
	v_lshlrev_b32_e32 v212, 16, v161
	v_and_b32_e32 v213, 0xffff0000, v161
	v_pk_fma_f32 v[214:215], v[14:15], v[202:203], v[6:7]
	v_pk_fma_f32 v[216:217], v[14:15], v[204:205], v[6:7]
	v_pk_fma_f32 v[236:237], v[14:15], v[206:207], v[6:7]
	v_pk_fma_f32 v[214:215], v[22:23], v[204:205], v[214:215]
	v_pk_fma_f32 v[216:217], v[22:23], v[206:207], v[216:217]
	v_pk_fma_f32 v[236:237], v[22:23], v[208:209], v[236:237]
	v_pk_fma_f32 v[214:215], v[30:31], v[206:207], v[214:215]
	v_pk_fma_f32 v[216:217], v[30:31], v[208:209], v[216:217]
	v_pk_fma_f32 v[236:237], v[30:31], v[210:211], v[236:237]
	v_pk_fma_f32 v[214:215], v[38:39], v[208:209], v[214:215]
	v_pk_fma_f32 v[216:217], v[38:39], v[210:211], v[216:217]
	v_pk_fma_f32 v[236:237], v[38:39], v[212:213], v[236:237]
	v_pk_mul_f32 v[202:203], v[214:215], s[42:43]
	v_pk_mul_f32 v[204:205], v[216:217], s[42:43]
	v_pk_mul_f32 v[206:207], v[236:237], s[42:43]
	v_exp_f32_e32 v202, v202
	v_exp_f32_e32 v203, v203
	v_exp_f32_e32 v204, v204
	v_exp_f32_e32 v205, v205
	v_exp_f32_e32 v206, v206
	v_exp_f32_e32 v207, v207
	s_nop 0
	v_pk_add_f32 v[202:203], v[202:203], 1.0 op_sel_hi:[1,0]
	v_pk_add_f32 v[204:205], v[204:205], 1.0 op_sel_hi:[1,0]
	v_pk_add_f32 v[206:207], v[206:207], 1.0 op_sel_hi:[1,0]
	v_rcp_f32_e32 v202, v202
	v_rcp_f32_e32 v203, v203
	v_rcp_f32_e32 v204, v204
	v_rcp_f32_e32 v205, v205
	v_rcp_f32_e32 v206, v206
	v_rcp_f32_e32 v207, v207
	s_nop 0
	v_pk_mul_f32 v[214:215], v[214:215], v[202:203]
	v_pk_mul_f32 v[216:217], v[216:217], v[204:205]
	v_pk_mul_f32 v[236:237], v[236:237], v[206:207]
	v_cvt_pk_bf16_f32 v141, v214, v215
	v_cvt_pk_bf16_f32 v145, v216, v217
	v_cvt_pk_bf16_f32 v149, v236, v237
	v_lshlrev_b32_e32 v202, 16, v142
	v_and_b32_e32 v203, 0xffff0000, v142
	v_lshlrev_b32_e32 v204, 16, v146
	v_and_b32_e32 v205, 0xffff0000, v146
	v_lshlrev_b32_e32 v206, 16, v150
	v_and_b32_e32 v207, 0xffff0000, v150
	v_lshlrev_b32_e32 v208, 16, v154
	v_and_b32_e32 v209, 0xffff0000, v154
	v_lshlrev_b32_e32 v210, 16, v158
	v_and_b32_e32 v211, 0xffff0000, v158
	v_lshlrev_b32_e32 v212, 16, v162
	v_and_b32_e32 v213, 0xffff0000, v162
	v_pk_fma_f32 v[214:215], v[16:17], v[202:203], v[8:9]
	v_pk_fma_f32 v[216:217], v[16:17], v[204:205], v[8:9]
	v_pk_fma_f32 v[236:237], v[16:17], v[206:207], v[8:9]
	v_pk_fma_f32 v[214:215], v[24:25], v[204:205], v[214:215]
	v_pk_fma_f32 v[216:217], v[24:25], v[206:207], v[216:217]
	v_pk_fma_f32 v[236:237], v[24:25], v[208:209], v[236:237]
	v_pk_fma_f32 v[214:215], v[32:33], v[206:207], v[214:215]
	v_pk_fma_f32 v[216:217], v[32:33], v[208:209], v[216:217]
	v_pk_fma_f32 v[236:237], v[32:33], v[210:211], v[236:237]
	v_pk_fma_f32 v[214:215], v[40:41], v[208:209], v[214:215]
	v_pk_fma_f32 v[216:217], v[40:41], v[210:211], v[216:217]
	v_pk_fma_f32 v[236:237], v[40:41], v[212:213], v[236:237]
	v_pk_mul_f32 v[202:203], v[214:215], s[42:43]
	v_pk_mul_f32 v[204:205], v[216:217], s[42:43]
	v_pk_mul_f32 v[206:207], v[236:237], s[42:43]
	v_exp_f32_e32 v202, v202
	v_exp_f32_e32 v203, v203
	v_exp_f32_e32 v204, v204
	v_exp_f32_e32 v205, v205
	v_exp_f32_e32 v206, v206
	v_exp_f32_e32 v207, v207
	s_nop 0
	v_pk_add_f32 v[202:203], v[202:203], 1.0 op_sel_hi:[1,0]
	v_pk_add_f32 v[204:205], v[204:205], 1.0 op_sel_hi:[1,0]
	v_pk_add_f32 v[206:207], v[206:207], 1.0 op_sel_hi:[1,0]
	v_rcp_f32_e32 v202, v202
	v_rcp_f32_e32 v203, v203
	v_rcp_f32_e32 v204, v204
	v_rcp_f32_e32 v205, v205
	v_rcp_f32_e32 v206, v206
	v_rcp_f32_e32 v207, v207
	s_nop 0
	v_pk_mul_f32 v[214:215], v[214:215], v[202:203]
	v_pk_mul_f32 v[216:217], v[216:217], v[204:205]
	v_pk_mul_f32 v[236:237], v[236:237], v[206:207]
	v_cvt_pk_bf16_f32 v142, v214, v215
	v_cvt_pk_bf16_f32 v146, v216, v217
	v_cvt_pk_bf16_f32 v150, v236, v237
	v_lshlrev_b32_e32 v202, 16, v143
	v_and_b32_e32 v203, 0xffff0000, v143
	v_lshlrev_b32_e32 v204, 16, v147
	v_and_b32_e32 v205, 0xffff0000, v147
	v_lshlrev_b32_e32 v206, 16, v151
	v_and_b32_e32 v207, 0xffff0000, v151
	v_lshlrev_b32_e32 v208, 16, v155
	v_and_b32_e32 v209, 0xffff0000, v155
	v_lshlrev_b32_e32 v210, 16, v159
	v_and_b32_e32 v211, 0xffff0000, v159
	v_lshlrev_b32_e32 v212, 16, v163
	v_and_b32_e32 v213, 0xffff0000, v163
	v_pk_fma_f32 v[214:215], v[18:19], v[202:203], v[10:11]
	v_pk_fma_f32 v[216:217], v[18:19], v[204:205], v[10:11]
	v_pk_fma_f32 v[236:237], v[18:19], v[206:207], v[10:11]
	v_pk_fma_f32 v[214:215], v[26:27], v[204:205], v[214:215]
	v_pk_fma_f32 v[216:217], v[26:27], v[206:207], v[216:217]
	v_pk_fma_f32 v[236:237], v[26:27], v[208:209], v[236:237]
	v_pk_fma_f32 v[214:215], v[34:35], v[206:207], v[214:215]
	v_pk_fma_f32 v[216:217], v[34:35], v[208:209], v[216:217]
	v_pk_fma_f32 v[236:237], v[34:35], v[210:211], v[236:237]
	v_pk_fma_f32 v[214:215], v[42:43], v[208:209], v[214:215]
	v_pk_fma_f32 v[216:217], v[42:43], v[210:211], v[216:217]
	v_pk_fma_f32 v[236:237], v[42:43], v[212:213], v[236:237]
	v_pk_mul_f32 v[202:203], v[214:215], s[42:43]
	v_pk_mul_f32 v[204:205], v[216:217], s[42:43]
	v_pk_mul_f32 v[206:207], v[236:237], s[42:43]
	v_exp_f32_e32 v202, v202
	v_exp_f32_e32 v203, v203
	v_exp_f32_e32 v204, v204
	v_exp_f32_e32 v205, v205
	v_exp_f32_e32 v206, v206
	v_exp_f32_e32 v207, v207
	s_nop 0
	v_pk_add_f32 v[202:203], v[202:203], 1.0 op_sel_hi:[1,0]
	v_pk_add_f32 v[204:205], v[204:205], 1.0 op_sel_hi:[1,0]
	v_pk_add_f32 v[206:207], v[206:207], 1.0 op_sel_hi:[1,0]
	v_rcp_f32_e32 v202, v202
	v_rcp_f32_e32 v203, v203
	v_rcp_f32_e32 v204, v204
	v_rcp_f32_e32 v205, v205
	v_rcp_f32_e32 v206, v206
	v_rcp_f32_e32 v207, v207
	s_nop 0
	v_pk_mul_f32 v[214:215], v[214:215], v[202:203]
	v_pk_mul_f32 v[216:217], v[216:217], v[204:205]
	v_pk_mul_f32 v[236:237], v[236:237], v[206:207]
	v_cvt_pk_bf16_f32 v143, v214, v215
	v_cvt_pk_bf16_f32 v147, v216, v217
	v_cvt_pk_bf16_f32 v151, v236, v237
	v_add_u32_e32 v0, 48, v238
	v_add_u32_e32 v1, s22, v0
	v_add_u32_e32 v2, 0x1000, v240
	v_mad_u32_u24 v1, v1, s23, v2
	global_store_dwordx4 v1, v[140:143], s[96:97]
	v_add_u32_e32 v1, 0x3400, v1
	global_store_dwordx4 v1, v[144:147], s[96:97]
	v_add_u32_e32 v1, 0x3400, v1
	global_store_dwordx4 v1, v[148:151], s[96:97]
	s_waitcnt vmcnt(15)
	v_add_u32_e32 v0, 60, v238
	v_cmp_eq_u32_e32 vcc, 64, v0
	s_nop 1
	v_cndmask_b32_e32 v164, v164, v3, vcc
	v_cndmask_b32_e32 v165, v165, v3, vcc
	v_cndmask_b32_e32 v166, v166, v3, vcc
	v_cndmask_b32_e32 v167, v167, v3, vcc
	v_cndmask_b32_e32 v168, v168, v3, vcc
	v_cndmask_b32_e32 v169, v169, v3, vcc
	v_cndmask_b32_e32 v170, v170, v3, vcc
	v_cndmask_b32_e32 v171, v171, v3, vcc
	v_cndmask_b32_e32 v172, v172, v3, vcc
	v_cndmask_b32_e32 v173, v173, v3, vcc
	v_cndmask_b32_e32 v174, v174, v3, vcc
	v_cndmask_b32_e32 v175, v175, v3, vcc
	v_lshlrev_b32_e32 v202, 16, v164
	v_and_b32_e32 v203, 0xffff0000, v164
	v_lshlrev_b32_e32 v204, 16, v168
	v_and_b32_e32 v205, 0xffff0000, v168
	v_lshlrev_b32_e32 v206, 16, v172
	v_and_b32_e32 v207, 0xffff0000, v172
	v_lshlrev_b32_e32 v208, 16, v176
	v_and_b32_e32 v209, 0xffff0000, v176
	v_lshlrev_b32_e32 v210, 16, v180
	v_and_b32_e32 v211, 0xffff0000, v180
	v_lshlrev_b32_e32 v212, 16, v184
	v_and_b32_e32 v213, 0xffff0000, v184
	v_pk_fma_f32 v[214:215], v[12:13], v[202:203], v[4:5]
	v_pk_fma_f32 v[216:217], v[12:13], v[204:205], v[4:5]
	v_pk_fma_f32 v[236:237], v[12:13], v[206:207], v[4:5]
	v_pk_fma_f32 v[214:215], v[20:21], v[204:205], v[214:215]
	v_pk_fma_f32 v[216:217], v[20:21], v[206:207], v[216:217]
	v_pk_fma_f32 v[236:237], v[20:21], v[208:209], v[236:237]
	v_pk_fma_f32 v[214:215], v[28:29], v[206:207], v[214:215]
	v_pk_fma_f32 v[216:217], v[28:29], v[208:209], v[216:217]
	v_pk_fma_f32 v[236:237], v[28:29], v[210:211], v[236:237]
	v_pk_fma_f32 v[214:215], v[36:37], v[208:209], v[214:215]
	v_pk_fma_f32 v[216:217], v[36:37], v[210:211], v[216:217]
	v_pk_fma_f32 v[236:237], v[36:37], v[212:213], v[236:237]
	v_pk_mul_f32 v[202:203], v[214:215], s[42:43]
	v_pk_mul_f32 v[204:205], v[216:217], s[42:43]
	v_pk_mul_f32 v[206:207], v[236:237], s[42:43]
	v_exp_f32_e32 v202, v202
	v_exp_f32_e32 v203, v203
	v_exp_f32_e32 v204, v204
	v_exp_f32_e32 v205, v205
	v_exp_f32_e32 v206, v206
	v_exp_f32_e32 v207, v207
	s_nop 0
	v_pk_add_f32 v[202:203], v[202:203], 1.0 op_sel_hi:[1,0]
	v_pk_add_f32 v[204:205], v[204:205], 1.0 op_sel_hi:[1,0]
	v_pk_add_f32 v[206:207], v[206:207], 1.0 op_sel_hi:[1,0]
	v_rcp_f32_e32 v202, v202
	v_rcp_f32_e32 v203, v203
	v_rcp_f32_e32 v204, v204
	v_rcp_f32_e32 v205, v205
	v_rcp_f32_e32 v206, v206
	v_rcp_f32_e32 v207, v207
	s_nop 0
	v_pk_mul_f32 v[214:215], v[214:215], v[202:203]
	v_pk_mul_f32 v[216:217], v[216:217], v[204:205]
	v_pk_mul_f32 v[236:237], v[236:237], v[206:207]
	v_cvt_pk_bf16_f32 v164, v214, v215
	v_cvt_pk_bf16_f32 v168, v216, v217
	v_cvt_pk_bf16_f32 v172, v236, v237
	v_lshlrev_b32_e32 v202, 16, v165
	v_and_b32_e32 v203, 0xffff0000, v165
	v_lshlrev_b32_e32 v204, 16, v169
	v_and_b32_e32 v205, 0xffff0000, v169
	v_lshlrev_b32_e32 v206, 16, v173
	v_and_b32_e32 v207, 0xffff0000, v173
	v_lshlrev_b32_e32 v208, 16, v177
	v_and_b32_e32 v209, 0xffff0000, v177
	v_lshlrev_b32_e32 v210, 16, v181
	v_and_b32_e32 v211, 0xffff0000, v181
	v_lshlrev_b32_e32 v212, 16, v185
	v_and_b32_e32 v213, 0xffff0000, v185
	v_pk_fma_f32 v[214:215], v[14:15], v[202:203], v[6:7]
	v_pk_fma_f32 v[216:217], v[14:15], v[204:205], v[6:7]
	v_pk_fma_f32 v[236:237], v[14:15], v[206:207], v[6:7]
	v_pk_fma_f32 v[214:215], v[22:23], v[204:205], v[214:215]
	v_pk_fma_f32 v[216:217], v[22:23], v[206:207], v[216:217]
	v_pk_fma_f32 v[236:237], v[22:23], v[208:209], v[236:237]
	v_pk_fma_f32 v[214:215], v[30:31], v[206:207], v[214:215]
	v_pk_fma_f32 v[216:217], v[30:31], v[208:209], v[216:217]
	v_pk_fma_f32 v[236:237], v[30:31], v[210:211], v[236:237]
	v_pk_fma_f32 v[214:215], v[38:39], v[208:209], v[214:215]
	v_pk_fma_f32 v[216:217], v[38:39], v[210:211], v[216:217]
	v_pk_fma_f32 v[236:237], v[38:39], v[212:213], v[236:237]
	v_pk_mul_f32 v[202:203], v[214:215], s[42:43]
	v_pk_mul_f32 v[204:205], v[216:217], s[42:43]
	v_pk_mul_f32 v[206:207], v[236:237], s[42:43]
	v_exp_f32_e32 v202, v202
	v_exp_f32_e32 v203, v203
	v_exp_f32_e32 v204, v204
	v_exp_f32_e32 v205, v205
	v_exp_f32_e32 v206, v206
	v_exp_f32_e32 v207, v207
	s_nop 0
	v_pk_add_f32 v[202:203], v[202:203], 1.0 op_sel_hi:[1,0]
	v_pk_add_f32 v[204:205], v[204:205], 1.0 op_sel_hi:[1,0]
	v_pk_add_f32 v[206:207], v[206:207], 1.0 op_sel_hi:[1,0]
	v_rcp_f32_e32 v202, v202
	v_rcp_f32_e32 v203, v203
	v_rcp_f32_e32 v204, v204
	v_rcp_f32_e32 v205, v205
	v_rcp_f32_e32 v206, v206
	v_rcp_f32_e32 v207, v207
	s_nop 0
	v_pk_mul_f32 v[214:215], v[214:215], v[202:203]
	v_pk_mul_f32 v[216:217], v[216:217], v[204:205]
	v_pk_mul_f32 v[236:237], v[236:237], v[206:207]
	v_cvt_pk_bf16_f32 v165, v214, v215
	v_cvt_pk_bf16_f32 v169, v216, v217
	v_cvt_pk_bf16_f32 v173, v236, v237
	v_lshlrev_b32_e32 v202, 16, v166
	v_and_b32_e32 v203, 0xffff0000, v166
	v_lshlrev_b32_e32 v204, 16, v170
	v_and_b32_e32 v205, 0xffff0000, v170
	v_lshlrev_b32_e32 v206, 16, v174
	v_and_b32_e32 v207, 0xffff0000, v174
	v_lshlrev_b32_e32 v208, 16, v178
	v_and_b32_e32 v209, 0xffff0000, v178
	v_lshlrev_b32_e32 v210, 16, v182
	v_and_b32_e32 v211, 0xffff0000, v182
	v_lshlrev_b32_e32 v212, 16, v186
	v_and_b32_e32 v213, 0xffff0000, v186
	v_pk_fma_f32 v[214:215], v[16:17], v[202:203], v[8:9]
	v_pk_fma_f32 v[216:217], v[16:17], v[204:205], v[8:9]
	v_pk_fma_f32 v[236:237], v[16:17], v[206:207], v[8:9]
	v_pk_fma_f32 v[214:215], v[24:25], v[204:205], v[214:215]
	v_pk_fma_f32 v[216:217], v[24:25], v[206:207], v[216:217]
	v_pk_fma_f32 v[236:237], v[24:25], v[208:209], v[236:237]
	v_pk_fma_f32 v[214:215], v[32:33], v[206:207], v[214:215]
	v_pk_fma_f32 v[216:217], v[32:33], v[208:209], v[216:217]
	v_pk_fma_f32 v[236:237], v[32:33], v[210:211], v[236:237]
	v_pk_fma_f32 v[214:215], v[40:41], v[208:209], v[214:215]
	v_pk_fma_f32 v[216:217], v[40:41], v[210:211], v[216:217]
	v_pk_fma_f32 v[236:237], v[40:41], v[212:213], v[236:237]
	v_pk_mul_f32 v[202:203], v[214:215], s[42:43]
	v_pk_mul_f32 v[204:205], v[216:217], s[42:43]
	v_pk_mul_f32 v[206:207], v[236:237], s[42:43]
	v_exp_f32_e32 v202, v202
	v_exp_f32_e32 v203, v203
	v_exp_f32_e32 v204, v204
	v_exp_f32_e32 v205, v205
	v_exp_f32_e32 v206, v206
	v_exp_f32_e32 v207, v207
	s_nop 0
	v_pk_add_f32 v[202:203], v[202:203], 1.0 op_sel_hi:[1,0]
	v_pk_add_f32 v[204:205], v[204:205], 1.0 op_sel_hi:[1,0]
	v_pk_add_f32 v[206:207], v[206:207], 1.0 op_sel_hi:[1,0]
	v_rcp_f32_e32 v202, v202
	v_rcp_f32_e32 v203, v203
	v_rcp_f32_e32 v204, v204
	v_rcp_f32_e32 v205, v205
	v_rcp_f32_e32 v206, v206
	v_rcp_f32_e32 v207, v207
	s_nop 0
	v_pk_mul_f32 v[214:215], v[214:215], v[202:203]
	v_pk_mul_f32 v[216:217], v[216:217], v[204:205]
	v_pk_mul_f32 v[236:237], v[236:237], v[206:207]
	v_cvt_pk_bf16_f32 v166, v214, v215
	v_cvt_pk_bf16_f32 v170, v216, v217
	v_cvt_pk_bf16_f32 v174, v236, v237
	v_lshlrev_b32_e32 v202, 16, v167
	v_and_b32_e32 v203, 0xffff0000, v167
	v_lshlrev_b32_e32 v204, 16, v171
	v_and_b32_e32 v205, 0xffff0000, v171
	v_lshlrev_b32_e32 v206, 16, v175
	v_and_b32_e32 v207, 0xffff0000, v175
	v_lshlrev_b32_e32 v208, 16, v179
	v_and_b32_e32 v209, 0xffff0000, v179
	v_lshlrev_b32_e32 v210, 16, v183
	v_and_b32_e32 v211, 0xffff0000, v183
	v_lshlrev_b32_e32 v212, 16, v187
	v_and_b32_e32 v213, 0xffff0000, v187
	v_pk_fma_f32 v[214:215], v[18:19], v[202:203], v[10:11]
	v_pk_fma_f32 v[216:217], v[18:19], v[204:205], v[10:11]
	v_pk_fma_f32 v[236:237], v[18:19], v[206:207], v[10:11]
	v_pk_fma_f32 v[214:215], v[26:27], v[204:205], v[214:215]
	v_pk_fma_f32 v[216:217], v[26:27], v[206:207], v[216:217]
	v_pk_fma_f32 v[236:237], v[26:27], v[208:209], v[236:237]
	v_pk_fma_f32 v[214:215], v[34:35], v[206:207], v[214:215]
	v_pk_fma_f32 v[216:217], v[34:35], v[208:209], v[216:217]
	v_pk_fma_f32 v[236:237], v[34:35], v[210:211], v[236:237]
	v_pk_fma_f32 v[214:215], v[42:43], v[208:209], v[214:215]
	v_pk_fma_f32 v[216:217], v[42:43], v[210:211], v[216:217]
	v_pk_fma_f32 v[236:237], v[42:43], v[212:213], v[236:237]
	v_pk_mul_f32 v[202:203], v[214:215], s[42:43]
	v_pk_mul_f32 v[204:205], v[216:217], s[42:43]
	v_pk_mul_f32 v[206:207], v[236:237], s[42:43]
	v_exp_f32_e32 v202, v202
	v_exp_f32_e32 v203, v203
	v_exp_f32_e32 v204, v204
	v_exp_f32_e32 v205, v205
	v_exp_f32_e32 v206, v206
	v_exp_f32_e32 v207, v207
	s_nop 0
	v_pk_add_f32 v[202:203], v[202:203], 1.0 op_sel_hi:[1,0]
	v_pk_add_f32 v[204:205], v[204:205], 1.0 op_sel_hi:[1,0]
	v_pk_add_f32 v[206:207], v[206:207], 1.0 op_sel_hi:[1,0]
	v_rcp_f32_e32 v202, v202
	v_rcp_f32_e32 v203, v203
	v_rcp_f32_e32 v204, v204
	v_rcp_f32_e32 v205, v205
	v_rcp_f32_e32 v206, v206
	v_rcp_f32_e32 v207, v207
	s_nop 0
	v_pk_mul_f32 v[214:215], v[214:215], v[202:203]
	v_pk_mul_f32 v[216:217], v[216:217], v[204:205]
	v_pk_mul_f32 v[236:237], v[236:237], v[206:207]
	v_cvt_pk_bf16_f32 v167, v214, v215
	v_cvt_pk_bf16_f32 v171, v216, v217
	v_cvt_pk_bf16_f32 v175, v236, v237
	v_add_u32_e32 v0, 60, v238
	v_cmp_eq_u32_e32 vcc, 64, v0
	v_add_u32_e32 v1, s22, v0
	v_mov_b32_e32 v2, 0x200
	v_cndmask_b32_e32 v1, v1, v2, vcc
	v_cmp_gt_u32_e32 vcc, 65, v0
	s_and_saveexec_b64 s[38:39], vcc
	v_add_u32_e32 v2, 0x1000, v240
	v_mad_u32_u24 v1, v1, s23, v2
	global_store_dwordx4 v1, v[164:167], s[96:97]
	v_add_u32_e32 v1, 0x3400, v1
	global_store_dwordx4 v1, v[168:171], s[96:97]
	v_add_u32_e32 v1, 0x3400, v1
	global_store_dwordx4 v1, v[172:175], s[96:97]
	s_waitcnt vmcnt(0)
